# NA attention loops: 16 exec-masked bias-table LDS reads per tile (each with its own lgkmcnt(0)) replaced by unconditional reads + v_cndmask selects
# speedup vs baseline: 1.0160x; 1.0060x over previous
.LBB0_597:
	s_andn2_b64 vcc, exec, s[74:75]
	s_cbranch_vccnz .LBB0_633
	s_add_i32 s74, s80, s83
	s_add_i32 s74, s74, -2
	s_cmp_gt_u32 s74, 7
	s_cbranch_scc1 .LBB0_632
	ds_read_b32 v64, v198
	ds_read_b32 v65, v198 offset:4
	ds_read_b32 v66, v198 offset:8
	ds_read_b32 v67, v198 offset:12
	ds_read_b32 v68, v198 offset:32
	ds_read_b32 v69, v198 offset:36
	ds_read_b32 v70, v198 offset:40
	ds_read_b32 v71, v198 offset:44
	ds_read_b32 v72, v198 offset:64
	ds_read_b32 v73, v198 offset:68
	ds_read_b32 v74, v198 offset:72
	ds_read_b32 v75, v198 offset:76
	ds_read_b32 v76, v198 offset:96
	ds_read_b32 v77, v198 offset:100
	ds_read_b32 v78, v198 offset:104
	ds_read_b32 v79, v198 offset:108
	s_waitcnt lgkmcnt(0)
	ds_read_b32 v14, v198 offset:128
	ds_read_b32 v15, v198 offset:132
	ds_read_b32 v17, v198 offset:136
	ds_read_b32 v18, v198 offset:140
	ds_read_b32 v19, v198 offset:160
	ds_read_b32 v20, v198 offset:164
	ds_read_b32 v21, v198 offset:168
	ds_read_b32 v22, v198 offset:172
	ds_read_b32 v23, v198 offset:192
	ds_read_b32 v24, v198 offset:196
	ds_read_b32 v25, v198 offset:200
	ds_read_b32 v26, v198 offset:204
	ds_read_b32 v27, v198 offset:224
	ds_read_b32 v28, v198 offset:228
	ds_read_b32 v30, v198 offset:232
	ds_read_b32 v29, v198 offset:236
	v_sub_f32_e32 v64, v64, v231
	v_add_f32_e32 v64, v112, v64
	v_cndmask_b32_e64 v64, v16, v64, s[6:7]
	v_sub_f32_e32 v65, v65, v231
	v_add_f32_e32 v65, v113, v65
	v_cndmask_b32_e64 v65, v16, v65, s[10:11]
	v_sub_f32_e32 v66, v66, v231
	v_add_f32_e32 v66, v114, v66
	v_cndmask_b32_e64 v66, v16, v66, s[14:15]
	v_sub_f32_e32 v67, v67, v231
	v_add_f32_e32 v67, v115, v67
	v_cndmask_b32_e64 v67, v16, v67, s[18:19]
	v_sub_f32_e32 v68, v68, v231
	v_add_f32_e32 v68, v116, v68
	v_cndmask_b32_e64 v68, v16, v68, s[22:23]
	v_sub_f32_e32 v69, v69, v231
	v_add_f32_e32 v69, v117, v69
	v_cndmask_b32_e64 v69, v16, v69, s[26:27]
	v_sub_f32_e32 v70, v70, v231
	v_add_f32_e32 v70, v118, v70
	v_cndmask_b32_e64 v70, v16, v70, s[30:31]
	v_sub_f32_e32 v71, v71, v231
	v_add_f32_e32 v71, v119, v71
	v_cndmask_b32_e64 v71, v16, v71, s[36:37]
	v_sub_f32_e32 v72, v72, v231
	v_add_f32_e32 v72, v120, v72
	v_cndmask_b32_e64 v72, v16, v72, s[40:41]
	v_sub_f32_e32 v73, v73, v231
	v_add_f32_e32 v73, v121, v73
	v_cndmask_b32_e64 v73, v16, v73, s[44:45]
	v_sub_f32_e32 v74, v74, v231
	v_add_f32_e32 v74, v122, v74
	v_cndmask_b32_e64 v74, v16, v74, s[48:49]
	v_sub_f32_e32 v75, v75, v231
	v_add_f32_e32 v75, v123, v75
	v_cndmask_b32_e64 v75, v16, v75, s[52:53]
	v_sub_f32_e32 v76, v76, v231
	v_add_f32_e32 v76, v124, v76
	v_cndmask_b32_e64 v76, v16, v76, s[56:57]
	v_sub_f32_e32 v77, v77, v231
	v_add_f32_e32 v77, v125, v77
	v_cndmask_b32_e64 v77, v16, v77, s[60:61]
	v_sub_f32_e32 v78, v78, v231
	v_add_f32_e32 v78, v126, v78
	v_cndmask_b32_e64 v78, v16, v78, s[64:65]
	v_sub_f32_e32 v79, v79, v231
	v_add_f32_e32 v79, v127, v79
	v_cndmask_b32_e64 v79, v16, v79, s[68:69]
	s_waitcnt lgkmcnt(14)
	v_sub_f32_e32 v14, v14, v231
	v_add_f32_e32 v14, v96, v14
	v_cndmask_b32_e64 v80, v16, v14, s[8:9]
	v_sub_f32_e32 v14, v15, v231
	v_add_f32_e32 v14, v97, v14
	v_cndmask_b32_e64 v81, v16, v14, s[12:13]
	s_waitcnt lgkmcnt(13)
	v_sub_f32_e32 v14, v17, v231
	v_add_f32_e32 v14, v98, v14
	v_cndmask_b32_e64 v82, v16, v14, s[16:17]
	s_waitcnt lgkmcnt(12)
	v_sub_f32_e32 v14, v18, v231
	v_add_f32_e32 v14, v99, v14
	v_cndmask_b32_e64 v83, v16, v14, s[20:21]
	s_waitcnt lgkmcnt(11)
	v_sub_f32_e32 v14, v19, v231
	v_add_f32_e32 v14, v100, v14
	v_cndmask_b32_e64 v84, v16, v14, s[24:25]
	s_waitcnt lgkmcnt(10)
	v_sub_f32_e32 v14, v20, v231
	v_add_f32_e32 v14, v101, v14
	v_cndmask_b32_e64 v85, v16, v14, s[28:29]
	s_waitcnt lgkmcnt(9)
	v_sub_f32_e32 v14, v21, v231
	v_add_f32_e32 v14, v102, v14
	v_cndmask_b32_e64 v86, v16, v14, s[34:35]
	s_waitcnt lgkmcnt(8)
	v_sub_f32_e32 v14, v22, v231
	v_add_f32_e32 v14, v103, v14
	v_cndmask_b32_e64 v87, v16, v14, s[38:39]
	s_waitcnt lgkmcnt(7)
	v_sub_f32_e32 v14, v23, v231
	v_add_f32_e32 v14, v104, v14
	v_cndmask_b32_e64 v88, v16, v14, s[42:43]
	s_waitcnt lgkmcnt(6)
	v_sub_f32_e32 v14, v24, v231
	v_add_f32_e32 v14, v105, v14
	v_cndmask_b32_e64 v89, v16, v14, s[46:47]
	s_waitcnt lgkmcnt(5)
	v_sub_f32_e32 v14, v25, v231
	v_add_f32_e32 v14, v106, v14
	v_cndmask_b32_e64 v90, v16, v14, s[50:51]
	s_waitcnt lgkmcnt(4)
	v_sub_f32_e32 v14, v26, v231
	v_add_f32_e32 v14, v107, v14
	v_cndmask_b32_e64 v91, v16, v14, s[54:55]
	s_waitcnt lgkmcnt(3)
	v_sub_f32_e32 v14, v27, v231
	v_add_f32_e32 v14, v108, v14
	v_cndmask_b32_e64 v92, v16, v14, s[58:59]
	s_waitcnt lgkmcnt(2)
	v_sub_f32_e32 v14, v28, v231
	v_add_f32_e32 v14, v109, v14
	v_cndmask_b32_e64 v93, v16, v14, s[62:63]
	s_waitcnt lgkmcnt(1)
	v_sub_f32_e32 v14, v30, v231
	v_add_f32_e32 v14, v110, v14
	v_cndmask_b32_e64 v94, v16, v14, s[66:67]
	s_waitcnt lgkmcnt(0)
	v_sub_f32_e32 v14, v29, v231
	v_add_f32_e32 v14, v111, v14
	v_cndmask_b32_e64 v95, v16, v14, s[70:71]
	s_branch .LBB0_633

.LBB0_642:
	s_andn2_b64 vcc, exec, s[74:75]
	s_cbranch_vccnz .LBB0_678
	s_add_i32 s2, s80, s83
	s_add_i32 s2, s2, -1
	s_cmp_gt_u32 s2, 7
	s_cbranch_scc1 .LBB0_677
	ds_read_b32 v64, v198 offset:124
	ds_read_b32 v65, v198 offset:128
	ds_read_b32 v66, v198 offset:132
	ds_read_b32 v67, v198 offset:136
	ds_read_b32 v68, v198 offset:156
	ds_read_b32 v69, v198 offset:160
	ds_read_b32 v70, v198 offset:164
	ds_read_b32 v71, v198 offset:168
	ds_read_b32 v72, v198 offset:188
	ds_read_b32 v73, v198 offset:192
	ds_read_b32 v74, v198 offset:196
	ds_read_b32 v75, v198 offset:200
	ds_read_b32 v76, v198 offset:220
	ds_read_b32 v77, v198 offset:224
	ds_read_b32 v78, v198 offset:228
	ds_read_b32 v79, v198 offset:232
	s_waitcnt lgkmcnt(0)
	ds_read_b32 v17, v198 offset:252
	ds_read_b32 v18, v198 offset:256
	ds_read_b32 v19, v198 offset:260
	ds_read_b32 v20, v198 offset:264
	ds_read_b32 v21, v198 offset:284
	ds_read_b32 v22, v198 offset:288
	ds_read_b32 v23, v198 offset:292
	ds_read_b32 v24, v198 offset:296
	ds_read_b32 v25, v198 offset:316
	ds_read_b32 v26, v198 offset:320
	ds_read_b32 v27, v198 offset:324
	ds_read_b32 v28, v198 offset:328
	ds_read_b32 v29, v198 offset:348
	ds_read_b32 v30, v198 offset:352
	ds_read_b32 v94, v198 offset:356
	ds_read_b32 v31, v198 offset:360
	v_sub_f32_e32 v64, v64, v231
	v_add_f32_e32 v64, v112, v64
	v_cndmask_b32_e64 v64, v16, v64, s[6:7]
	v_sub_f32_e32 v65, v65, v231
	v_add_f32_e32 v65, v113, v65
	v_cndmask_b32_e64 v65, v16, v65, s[10:11]
	v_sub_f32_e32 v66, v66, v231
	v_add_f32_e32 v66, v114, v66
	v_cndmask_b32_e64 v66, v16, v66, s[14:15]
	v_sub_f32_e32 v67, v67, v231
	v_add_f32_e32 v67, v115, v67
	v_cndmask_b32_e64 v67, v16, v67, s[18:19]
	v_sub_f32_e32 v68, v68, v231
	v_add_f32_e32 v68, v116, v68
	v_cndmask_b32_e64 v68, v16, v68, s[22:23]
	v_sub_f32_e32 v69, v69, v231
	v_add_f32_e32 v69, v117, v69
	v_cndmask_b32_e64 v69, v16, v69, s[26:27]
	v_sub_f32_e32 v70, v70, v231
	v_add_f32_e32 v70, v118, v70
	v_cndmask_b32_e64 v70, v16, v70, s[30:31]
	v_sub_f32_e32 v71, v71, v231
	v_add_f32_e32 v71, v119, v71
	v_cndmask_b32_e64 v71, v16, v71, s[36:37]
	v_sub_f32_e32 v72, v72, v231
	v_add_f32_e32 v72, v120, v72
	v_cndmask_b32_e64 v72, v16, v72, s[40:41]
	v_sub_f32_e32 v73, v73, v231
	v_add_f32_e32 v73, v121, v73
	v_cndmask_b32_e64 v73, v16, v73, s[44:45]
	v_sub_f32_e32 v74, v74, v231
	v_add_f32_e32 v74, v122, v74
	v_cndmask_b32_e64 v74, v16, v74, s[48:49]
	v_sub_f32_e32 v75, v75, v231
	v_add_f32_e32 v75, v123, v75
	v_cndmask_b32_e64 v75, v16, v75, s[52:53]
	v_sub_f32_e32 v76, v76, v231
	v_add_f32_e32 v76, v124, v76
	v_cndmask_b32_e64 v76, v16, v76, s[56:57]
	v_sub_f32_e32 v77, v77, v231
	v_add_f32_e32 v77, v125, v77
	v_cndmask_b32_e64 v77, v16, v77, s[60:61]
	v_sub_f32_e32 v78, v78, v231
	v_add_f32_e32 v78, v126, v78
	v_cndmask_b32_e64 v78, v16, v78, s[64:65]
	v_sub_f32_e32 v79, v79, v231
	v_add_f32_e32 v79, v127, v79
	v_cndmask_b32_e64 v79, v16, v79, s[68:69]
	s_waitcnt lgkmcnt(14)
	v_sub_f32_e32 v17, v17, v231
	v_add_f32_e32 v17, v96, v17
	v_cndmask_b32_e64 v80, v16, v17, s[8:9]
	v_sub_f32_e32 v17, v18, v231
	v_add_f32_e32 v17, v97, v17
	v_cndmask_b32_e64 v81, v16, v17, s[12:13]
	s_waitcnt lgkmcnt(13)
	v_sub_f32_e32 v17, v19, v231
	v_add_f32_e32 v17, v98, v17
	v_cndmask_b32_e64 v82, v16, v17, s[16:17]
	s_waitcnt lgkmcnt(12)
	v_sub_f32_e32 v17, v20, v231
	v_add_f32_e32 v17, v99, v17
	v_cndmask_b32_e64 v83, v16, v17, s[20:21]
	s_waitcnt lgkmcnt(11)
	v_sub_f32_e32 v17, v21, v231
	v_add_f32_e32 v17, v100, v17
	v_cndmask_b32_e64 v84, v16, v17, s[24:25]
	s_waitcnt lgkmcnt(10)
	v_sub_f32_e32 v17, v22, v231
	v_add_f32_e32 v17, v101, v17
	v_cndmask_b32_e64 v85, v16, v17, s[28:29]
	s_waitcnt lgkmcnt(9)
	v_sub_f32_e32 v17, v23, v231
	v_add_f32_e32 v17, v102, v17
	v_cndmask_b32_e64 v86, v16, v17, s[34:35]
	s_waitcnt lgkmcnt(8)
	v_sub_f32_e32 v17, v24, v231
	v_add_f32_e32 v17, v103, v17
	v_cndmask_b32_e64 v87, v16, v17, s[38:39]
	s_waitcnt lgkmcnt(7)
	v_sub_f32_e32 v17, v25, v231
	v_add_f32_e32 v17, v104, v17
	v_cndmask_b32_e64 v88, v16, v17, s[42:43]
	s_waitcnt lgkmcnt(6)
	v_sub_f32_e32 v17, v26, v231
	v_add_f32_e32 v17, v105, v17
	v_cndmask_b32_e64 v89, v16, v17, s[46:47]
	s_waitcnt lgkmcnt(5)
	v_sub_f32_e32 v17, v27, v231
	v_add_f32_e32 v17, v106, v17
	v_cndmask_b32_e64 v90, v16, v17, s[50:51]
	s_waitcnt lgkmcnt(4)
	v_sub_f32_e32 v17, v28, v231
	v_add_f32_e32 v17, v107, v17
	v_cndmask_b32_e64 v91, v16, v17, s[54:55]
	s_waitcnt lgkmcnt(3)
	v_sub_f32_e32 v17, v29, v231
	v_add_f32_e32 v17, v108, v17
	v_cndmask_b32_e64 v92, v16, v17, s[58:59]
	s_waitcnt lgkmcnt(2)
	v_sub_f32_e32 v17, v30, v231
	v_add_f32_e32 v17, v109, v17
	v_cndmask_b32_e64 v93, v16, v17, s[62:63]
	s_waitcnt lgkmcnt(1)
	v_sub_f32_e32 v17, v94, v231
	v_add_f32_e32 v17, v110, v17
	v_cndmask_b32_e64 v94, v16, v17, s[66:67]
	s_waitcnt lgkmcnt(0)
	v_sub_f32_e32 v17, v31, v231
	v_add_f32_e32 v17, v111, v17
	v_cndmask_b32_e64 v95, v16, v17, s[70:71]
	s_branch .LBB0_678

.LBB0_697:
	s_andn2_b64 vcc, exec, s[0:1]
	s_cbranch_vccnz .LBB0_733
	s_add_i32 s0, s74, s86
	s_add_i32 s0, s0, -7
	s_cmp_gt_u32 s0, 7
	s_cbranch_scc1 .LBB0_732
	ds_read_b32 v64, v14
	ds_read_b32 v65, v14 offset:4
	ds_read_b32 v66, v14 offset:8
	ds_read_b32 v67, v14 offset:12
	ds_read_b32 v68, v14 offset:32
	ds_read_b32 v69, v14 offset:36
	ds_read_b32 v70, v14 offset:40
	ds_read_b32 v71, v14 offset:44
	ds_read_b32 v72, v14 offset:64
	ds_read_b32 v73, v14 offset:68
	ds_read_b32 v74, v14 offset:72
	ds_read_b32 v75, v14 offset:76
	ds_read_b32 v76, v14 offset:96
	ds_read_b32 v77, v14 offset:100
	ds_read_b32 v78, v14 offset:104
	ds_read_b32 v79, v14 offset:108
	s_waitcnt lgkmcnt(0)
	ds_read_b32 v17, v14 offset:128
	ds_read_b32 v18, v14 offset:132
	ds_read_b32 v19, v14 offset:136
	ds_read_b32 v20, v14 offset:140
	ds_read_b32 v21, v14 offset:160
	ds_read_b32 v22, v14 offset:164
	ds_read_b32 v23, v14 offset:168
	ds_read_b32 v24, v14 offset:172
	ds_read_b32 v25, v14 offset:192
	ds_read_b32 v26, v14 offset:196
	ds_read_b32 v27, v14 offset:200
	ds_read_b32 v28, v14 offset:204
	ds_read_b32 v29, v14 offset:224
	ds_read_b32 v30, v14 offset:228
	ds_read_b32 v94, v14 offset:232
	ds_read_b32 v31, v14 offset:236
	v_sub_f32_e32 v64, v64, v231
	v_add_f32_e32 v64, v112, v64
	v_cndmask_b32_e64 v64, v16, v64, s[6:7]
	v_sub_f32_e32 v65, v65, v231
	v_add_f32_e32 v65, v113, v65
	v_cndmask_b32_e64 v65, v16, v65, s[10:11]
	v_sub_f32_e32 v66, v66, v231
	v_add_f32_e32 v66, v114, v66
	v_cndmask_b32_e64 v66, v16, v66, s[14:15]
	v_sub_f32_e32 v67, v67, v231
	v_add_f32_e32 v67, v115, v67
	v_cndmask_b32_e64 v67, v16, v67, s[18:19]
	v_sub_f32_e32 v68, v68, v231
	v_add_f32_e32 v68, v116, v68
	v_cndmask_b32_e64 v68, v16, v68, s[22:23]
	v_sub_f32_e32 v69, v69, v231
	v_add_f32_e32 v69, v117, v69
	v_cndmask_b32_e64 v69, v16, v69, s[26:27]
	v_sub_f32_e32 v70, v70, v231
	v_add_f32_e32 v70, v118, v70
	v_cndmask_b32_e64 v70, v16, v70, s[30:31]
	v_sub_f32_e32 v71, v71, v231
	v_add_f32_e32 v71, v119, v71
	v_cndmask_b32_e64 v71, v16, v71, s[36:37]
	v_sub_f32_e32 v72, v72, v231
	v_add_f32_e32 v72, v120, v72
	v_cndmask_b32_e64 v72, v16, v72, s[40:41]
	v_sub_f32_e32 v73, v73, v231
	v_add_f32_e32 v73, v121, v73
	v_cndmask_b32_e64 v73, v16, v73, s[44:45]
	v_sub_f32_e32 v74, v74, v231
	v_add_f32_e32 v74, v122, v74
	v_cndmask_b32_e64 v74, v16, v74, s[48:49]
	v_sub_f32_e32 v75, v75, v231
	v_add_f32_e32 v75, v123, v75
	v_cndmask_b32_e64 v75, v16, v75, s[52:53]
	v_sub_f32_e32 v76, v76, v231
	v_add_f32_e32 v76, v124, v76
	v_cndmask_b32_e64 v76, v16, v76, s[56:57]
	v_sub_f32_e32 v77, v77, v231
	v_add_f32_e32 v77, v125, v77
	v_cndmask_b32_e64 v77, v16, v77, s[60:61]
	v_sub_f32_e32 v78, v78, v231
	v_add_f32_e32 v78, v126, v78
	v_cndmask_b32_e64 v78, v16, v78, s[64:65]
	v_sub_f32_e32 v79, v79, v231
	v_add_f32_e32 v79, v127, v79
	v_cndmask_b32_e64 v79, v16, v79, s[68:69]
	s_waitcnt lgkmcnt(14)
	v_sub_f32_e32 v17, v17, v231
	v_add_f32_e32 v17, v96, v17
	v_cndmask_b32_e64 v80, v16, v17, s[8:9]
	v_sub_f32_e32 v17, v18, v231
	v_add_f32_e32 v17, v97, v17
	v_cndmask_b32_e64 v81, v16, v17, s[12:13]
	s_waitcnt lgkmcnt(13)
	v_sub_f32_e32 v17, v19, v231
	v_add_f32_e32 v17, v98, v17
	v_cndmask_b32_e64 v82, v16, v17, s[16:17]
	s_waitcnt lgkmcnt(12)
	v_sub_f32_e32 v17, v20, v231
	v_add_f32_e32 v17, v99, v17
	v_cndmask_b32_e64 v83, v16, v17, s[20:21]
	s_waitcnt lgkmcnt(11)
	v_sub_f32_e32 v17, v21, v231
	v_add_f32_e32 v17, v100, v17
	v_cndmask_b32_e64 v84, v16, v17, s[24:25]
	s_waitcnt lgkmcnt(10)
	v_sub_f32_e32 v17, v22, v231
	v_add_f32_e32 v17, v101, v17
	v_cndmask_b32_e64 v85, v16, v17, s[28:29]
	s_waitcnt lgkmcnt(9)
	v_sub_f32_e32 v17, v23, v231
	v_add_f32_e32 v17, v102, v17
	v_cndmask_b32_e64 v86, v16, v17, s[34:35]
	s_waitcnt lgkmcnt(8)
	v_sub_f32_e32 v17, v24, v231
	v_add_f32_e32 v17, v103, v17
	v_cndmask_b32_e64 v87, v16, v17, s[38:39]
	s_waitcnt lgkmcnt(7)
	v_sub_f32_e32 v17, v25, v231
	v_add_f32_e32 v17, v104, v17
	v_cndmask_b32_e64 v88, v16, v17, s[42:43]
	s_waitcnt lgkmcnt(6)
	v_sub_f32_e32 v17, v26, v231
	v_add_f32_e32 v17, v105, v17
	v_cndmask_b32_e64 v89, v16, v17, s[46:47]
	s_waitcnt lgkmcnt(5)
	v_sub_f32_e32 v17, v27, v231
	v_add_f32_e32 v17, v106, v17
	v_cndmask_b32_e64 v90, v16, v17, s[50:51]
	s_waitcnt lgkmcnt(4)
	v_sub_f32_e32 v17, v28, v231
	v_add_f32_e32 v17, v107, v17
	v_cndmask_b32_e64 v91, v16, v17, s[54:55]
	s_waitcnt lgkmcnt(3)
	v_sub_f32_e32 v17, v29, v231
	v_add_f32_e32 v17, v108, v17
	v_cndmask_b32_e64 v92, v16, v17, s[58:59]
	s_waitcnt lgkmcnt(2)
	v_sub_f32_e32 v17, v30, v231
	v_add_f32_e32 v17, v109, v17
	v_cndmask_b32_e64 v93, v16, v17, s[62:63]
	s_waitcnt lgkmcnt(1)
	v_sub_f32_e32 v17, v94, v231
	v_add_f32_e32 v17, v110, v17
	v_cndmask_b32_e64 v94, v16, v17, s[66:67]
	s_waitcnt lgkmcnt(0)
	v_sub_f32_e32 v17, v31, v231
	v_add_f32_e32 v17, v111, v17
	v_cndmask_b32_e64 v95, v16, v17, s[70:71]
	s_branch .LBB0_733

.LBB0_755:
	s_add_i32 s0, s74, s86
	s_add_i32 s0, s0, -6
	s_cmp_gt_u32 s0, 7
	s_cbranch_scc1 .LBB0_789
	ds_read_b32 v64, v14 offset:124
	ds_read_b32 v65, v14 offset:128
	ds_read_b32 v66, v14 offset:132
	ds_read_b32 v67, v14 offset:136
	ds_read_b32 v68, v14 offset:156
	ds_read_b32 v69, v14 offset:160
	ds_read_b32 v70, v14 offset:164
	ds_read_b32 v71, v14 offset:168
	ds_read_b32 v72, v14 offset:188
	ds_read_b32 v73, v14 offset:192
	ds_read_b32 v74, v14 offset:196
	ds_read_b32 v75, v14 offset:200
	ds_read_b32 v76, v14 offset:220
	ds_read_b32 v77, v14 offset:224
	ds_read_b32 v78, v14 offset:228
	ds_read_b32 v79, v14 offset:232
	s_waitcnt lgkmcnt(0)
	ds_read_b32 v17, v14 offset:252
	ds_read_b32 v18, v14 offset:256
	ds_read_b32 v19, v14 offset:260
	ds_read_b32 v20, v14 offset:264
	ds_read_b32 v21, v14 offset:284
	ds_read_b32 v22, v14 offset:288
	ds_read_b32 v23, v14 offset:292
	ds_read_b32 v24, v14 offset:296
	ds_read_b32 v25, v14 offset:316
	ds_read_b32 v26, v14 offset:320
	ds_read_b32 v27, v14 offset:324
	ds_read_b32 v28, v14 offset:328
	ds_read_b32 v29, v14 offset:348
	ds_read_b32 v30, v14 offset:352
	ds_read_b32 v94, v14 offset:356
	ds_read_b32 v31, v14 offset:360
	v_sub_f32_e32 v64, v64, v231
	v_add_f32_e32 v64, v112, v64
	v_cndmask_b32_e64 v64, v16, v64, s[6:7]
	v_sub_f32_e32 v65, v65, v231
	v_add_f32_e32 v65, v113, v65
	v_cndmask_b32_e64 v65, v16, v65, s[10:11]
	v_sub_f32_e32 v66, v66, v231
	v_add_f32_e32 v66, v114, v66
	v_cndmask_b32_e64 v66, v16, v66, s[14:15]
	v_sub_f32_e32 v67, v67, v231
	v_add_f32_e32 v67, v115, v67
	v_cndmask_b32_e64 v67, v16, v67, s[18:19]
	v_sub_f32_e32 v68, v68, v231
	v_add_f32_e32 v68, v116, v68
	v_cndmask_b32_e64 v68, v16, v68, s[22:23]
	v_sub_f32_e32 v69, v69, v231
	v_add_f32_e32 v69, v117, v69
	v_cndmask_b32_e64 v69, v16, v69, s[26:27]
	v_sub_f32_e32 v70, v70, v231
	v_add_f32_e32 v70, v118, v70
	v_cndmask_b32_e64 v70, v16, v70, s[30:31]
	v_sub_f32_e32 v71, v71, v231
	v_add_f32_e32 v71, v119, v71
	v_cndmask_b32_e64 v71, v16, v71, s[36:37]
	v_sub_f32_e32 v72, v72, v231
	v_add_f32_e32 v72, v120, v72
	v_cndmask_b32_e64 v72, v16, v72, s[40:41]
	v_sub_f32_e32 v73, v73, v231
	v_add_f32_e32 v73, v121, v73
	v_cndmask_b32_e64 v73, v16, v73, s[44:45]
	v_sub_f32_e32 v74, v74, v231
	v_add_f32_e32 v74, v122, v74
	v_cndmask_b32_e64 v74, v16, v74, s[48:49]
	v_sub_f32_e32 v75, v75, v231
	v_add_f32_e32 v75, v123, v75
	v_cndmask_b32_e64 v75, v16, v75, s[52:53]
	v_sub_f32_e32 v76, v76, v231
	v_add_f32_e32 v76, v124, v76
	v_cndmask_b32_e64 v76, v16, v76, s[56:57]
	v_sub_f32_e32 v77, v77, v231
	v_add_f32_e32 v77, v125, v77
	v_cndmask_b32_e64 v77, v16, v77, s[60:61]
	v_sub_f32_e32 v78, v78, v231
	v_add_f32_e32 v78, v126, v78
	v_cndmask_b32_e64 v78, v16, v78, s[64:65]
	v_sub_f32_e32 v79, v79, v231
	v_add_f32_e32 v79, v127, v79
	v_cndmask_b32_e64 v79, v16, v79, s[68:69]
	s_waitcnt lgkmcnt(14)
	v_sub_f32_e32 v17, v17, v231
	v_add_f32_e32 v17, v96, v17
	v_cndmask_b32_e64 v80, v16, v17, s[8:9]
	v_sub_f32_e32 v17, v18, v231
	v_add_f32_e32 v17, v97, v17
	v_cndmask_b32_e64 v81, v16, v17, s[12:13]
	s_waitcnt lgkmcnt(13)
	v_sub_f32_e32 v17, v19, v231
	v_add_f32_e32 v17, v98, v17
	v_cndmask_b32_e64 v82, v16, v17, s[16:17]
	s_waitcnt lgkmcnt(12)
	v_sub_f32_e32 v17, v20, v231
	v_add_f32_e32 v17, v99, v17
	v_cndmask_b32_e64 v83, v16, v17, s[20:21]
	s_waitcnt lgkmcnt(11)
	v_sub_f32_e32 v17, v21, v231
	v_add_f32_e32 v17, v100, v17
	v_cndmask_b32_e64 v84, v16, v17, s[24:25]
	s_waitcnt lgkmcnt(10)
	v_sub_f32_e32 v17, v22, v231
	v_add_f32_e32 v17, v101, v17
	v_cndmask_b32_e64 v85, v16, v17, s[28:29]
	s_waitcnt lgkmcnt(9)
	v_sub_f32_e32 v17, v23, v231
	v_add_f32_e32 v17, v102, v17
	v_cndmask_b32_e64 v86, v16, v17, s[34:35]
	s_waitcnt lgkmcnt(8)
	v_sub_f32_e32 v17, v24, v231
	v_add_f32_e32 v17, v103, v17
	v_cndmask_b32_e64 v87, v16, v17, s[38:39]
	s_waitcnt lgkmcnt(7)
	v_sub_f32_e32 v17, v25, v231
	v_add_f32_e32 v17, v104, v17
	v_cndmask_b32_e64 v88, v16, v17, s[42:43]
	s_waitcnt lgkmcnt(6)
	v_sub_f32_e32 v17, v26, v231
	v_add_f32_e32 v17, v105, v17
	v_cndmask_b32_e64 v89, v16, v17, s[46:47]
	s_waitcnt lgkmcnt(5)
	v_sub_f32_e32 v17, v27, v231
	v_add_f32_e32 v17, v106, v17
	v_cndmask_b32_e64 v90, v16, v17, s[50:51]
	s_waitcnt lgkmcnt(4)
	v_sub_f32_e32 v17, v28, v231
	v_add_f32_e32 v17, v107, v17
	v_cndmask_b32_e64 v91, v16, v17, s[54:55]
	s_waitcnt lgkmcnt(3)
	v_sub_f32_e32 v17, v29, v231
	v_add_f32_e32 v17, v108, v17
	v_cndmask_b32_e64 v92, v16, v17, s[58:59]
	s_waitcnt lgkmcnt(2)
	v_sub_f32_e32 v17, v30, v231
	v_add_f32_e32 v17, v109, v17
	v_cndmask_b32_e64 v93, v16, v17, s[62:63]
	s_waitcnt lgkmcnt(1)
	v_sub_f32_e32 v17, v94, v231
	v_add_f32_e32 v17, v110, v17
	v_cndmask_b32_e64 v94, v16, v17, s[66:67]
	s_waitcnt lgkmcnt(0)
	v_sub_f32_e32 v17, v31, v231
	v_add_f32_e32 v17, v111, v17
	v_cndmask_b32_e64 v95, v16, v17, s[70:71]
	s_branch .LBB0_790
